# post0 rotary-table vectors requested at iteration top (verified -17us on the phase), on the rebalanced-prep / SSD-prefetch / gMLP-rebalance version
# speedup vs baseline: 1.0141x; 1.0003x over previous
.LBB0_332:
	s_or_b64 exec, exec, s[6:7]
	s_waitcnt lgkmcnt(0)
	s_lshl_b64 s[4:5], s[14:15], 11
	v_ashrrev_i32_e32 v64, 5, v177
	v_lshl_add_u32 v67, v64, 4, v179
	ds_read2_b32 v[70:71], v67 offset1:1
	ds_read2_b32 v[72:73], v67 offset0:2 offset1:3
	ds_read2_b32 v[74:75], v67 offset0:8 offset1:9
	ds_read2_b32 v[76:77], v67 offset0:10 offset1:11
	ds_read2_b32 v[78:79], v67 offset0:16 offset1:17
	ds_read2_b32 v[80:81], v67 offset0:18 offset1:19
	ds_read2_b32 v[82:83], v67 offset0:24 offset1:25
	ds_read2_b32 v[84:85], v67 offset0:26 offset1:27
	s_add_u32 s4, s10, s4
	s_addc_u32 s5, s11, s5
	s_add_u32 s4, s4, s18
	s_addc_u32 s5, s5, s19
	s_add_i32 s31, s31, 1
	v_readlane_b32 s6, v254, 41
	v_readlane_b32 s7, v254, 42
	v_and_b32_e32 v65, 31, v177
	v_lshlrev_b32_e32 v66, 8, v178
	v_lshl_add_u32 v66, v64, 10, v66
	v_lshl_add_u32 v66, v65, 1, v66
	v_add_u32_e32 v66, 0x11000, v66
	s_waitcnt lgkmcnt(0)
	v_rcp_f32_e32 v70, v70
	v_rcp_f32_e32 v71, v71
	v_rcp_f32_e32 v72, v72
	v_rcp_f32_e32 v73, v73
	v_rcp_f32_e32 v74, v74
	v_rcp_f32_e32 v75, v75
	v_rcp_f32_e32 v76, v76
	v_rcp_f32_e32 v77, v77
	v_rcp_f32_e32 v78, v78
	v_rcp_f32_e32 v79, v79
	v_rcp_f32_e32 v80, v80
	v_rcp_f32_e32 v81, v81
	v_rcp_f32_e32 v82, v82
	v_rcp_f32_e32 v83, v83
	v_rcp_f32_e32 v84, v84
	v_rcp_f32_e32 v85, v85
	s_nop 1
	v_mul_f32_e32 v0, v0, v70
	v_cvt_pk_bf16_f32 v0, v0, v193
	ds_write_b16 v66, v0 offset:0
	v_mul_f32_e32 v48, v48, v70
	v_cvt_pk_bf16_f32 v48, v48, v193
	ds_write_b16 v66, v48 offset:64
	v_mul_f32_e32 v32, v32, v70
	v_cvt_pk_bf16_f32 v32, v32, v193
	ds_write_b16 v66, v32 offset:128
	v_mul_f32_e32 v16, v16, v70
	v_cvt_pk_bf16_f32 v16, v16, v193
	ds_write_b16 v66, v16 offset:192
	v_mul_f32_e32 v1, v1, v71
	v_cvt_pk_bf16_f32 v1, v1, v193
	ds_write_b16 v66, v1 offset:256
	v_mul_f32_e32 v49, v49, v71
	v_cvt_pk_bf16_f32 v49, v49, v193
	ds_write_b16 v66, v49 offset:320
	v_mul_f32_e32 v33, v33, v71
	v_cvt_pk_bf16_f32 v33, v33, v193
	ds_write_b16 v66, v33 offset:384
	v_mul_f32_e32 v17, v17, v71
	v_cvt_pk_bf16_f32 v17, v17, v193
	ds_write_b16 v66, v17 offset:448
	s_waitcnt lgkmcnt(7)
	v_mul_f32_e32 v2, v2, v72
	v_cvt_pk_bf16_f32 v2, v2, v193
	ds_write_b16 v66, v2 offset:512
	v_mul_f32_e32 v50, v50, v72
	v_cvt_pk_bf16_f32 v50, v50, v193
	ds_write_b16 v66, v50 offset:576
	v_mul_f32_e32 v34, v34, v72
	v_cvt_pk_bf16_f32 v34, v34, v193
	ds_write_b16 v66, v34 offset:640
	v_mul_f32_e32 v18, v18, v72
	v_cvt_pk_bf16_f32 v18, v18, v193
	ds_write_b16 v66, v18 offset:704
	v_mul_f32_e32 v3, v3, v73
	v_cvt_pk_bf16_f32 v3, v3, v193
	ds_write_b16 v66, v3 offset:768
	v_mul_f32_e32 v51, v51, v73
	v_cvt_pk_bf16_f32 v51, v51, v193
	ds_write_b16 v66, v51 offset:832
	v_mul_f32_e32 v35, v35, v73
	v_cvt_pk_bf16_f32 v35, v35, v193
	ds_write_b16 v66, v35 offset:896
	v_mul_f32_e32 v19, v19, v73
	v_cvt_pk_bf16_f32 v19, v19, v193
	ds_write_b16 v66, v19 offset:960
	s_waitcnt lgkmcnt(7)
	v_mul_f32_e32 v4, v4, v74
	v_cvt_pk_bf16_f32 v4, v4, v193
	ds_write_b16 v66, v4 offset:2048
	v_mul_f32_e32 v52, v52, v74
	v_cvt_pk_bf16_f32 v52, v52, v193
	ds_write_b16 v66, v52 offset:2112
	v_mul_f32_e32 v36, v36, v74
	v_cvt_pk_bf16_f32 v36, v36, v193
	ds_write_b16 v66, v36 offset:2176
	v_mul_f32_e32 v20, v20, v74
	v_cvt_pk_bf16_f32 v20, v20, v193
	ds_write_b16 v66, v20 offset:2240
	v_mul_f32_e32 v5, v5, v75
	v_cvt_pk_bf16_f32 v5, v5, v193
	ds_write_b16 v66, v5 offset:2304
	v_mul_f32_e32 v53, v53, v75
	v_cvt_pk_bf16_f32 v53, v53, v193
	ds_write_b16 v66, v53 offset:2368
	v_mul_f32_e32 v37, v37, v75
	v_cvt_pk_bf16_f32 v37, v37, v193
	ds_write_b16 v66, v37 offset:2432
	v_mul_f32_e32 v21, v21, v75
	v_cvt_pk_bf16_f32 v21, v21, v193
	ds_write_b16 v66, v21 offset:2496
	s_waitcnt lgkmcnt(7)
	v_mul_f32_e32 v6, v6, v76
	v_cvt_pk_bf16_f32 v6, v6, v193
	ds_write_b16 v66, v6 offset:2560
	v_mul_f32_e32 v54, v54, v76
	v_cvt_pk_bf16_f32 v54, v54, v193
	ds_write_b16 v66, v54 offset:2624
	v_mul_f32_e32 v38, v38, v76
	v_cvt_pk_bf16_f32 v38, v38, v193
	ds_write_b16 v66, v38 offset:2688
	v_mul_f32_e32 v22, v22, v76
	v_cvt_pk_bf16_f32 v22, v22, v193
	ds_write_b16 v66, v22 offset:2752
	v_mul_f32_e32 v7, v7, v77
	v_cvt_pk_bf16_f32 v7, v7, v193
	ds_write_b16 v66, v7 offset:2816
	v_mul_f32_e32 v55, v55, v77
	v_cvt_pk_bf16_f32 v55, v55, v193
	ds_write_b16 v66, v55 offset:2880
	v_mul_f32_e32 v39, v39, v77
	v_cvt_pk_bf16_f32 v39, v39, v193
	ds_write_b16 v66, v39 offset:2944
	v_mul_f32_e32 v23, v23, v77
	v_cvt_pk_bf16_f32 v23, v23, v193
	ds_write_b16 v66, v23 offset:3008
	s_waitcnt lgkmcnt(7)
	v_mul_f32_e32 v8, v8, v78
	v_cvt_pk_bf16_f32 v8, v8, v193
	ds_write_b16 v66, v8 offset:4096
	v_mul_f32_e32 v56, v56, v78
	v_cvt_pk_bf16_f32 v56, v56, v193
	ds_write_b16 v66, v56 offset:4160
	v_mul_f32_e32 v40, v40, v78
	v_cvt_pk_bf16_f32 v40, v40, v193
	ds_write_b16 v66, v40 offset:4224
	v_mul_f32_e32 v24, v24, v78
	v_cvt_pk_bf16_f32 v24, v24, v193
	ds_write_b16 v66, v24 offset:4288
	v_mul_f32_e32 v9, v9, v79
	v_cvt_pk_bf16_f32 v9, v9, v193
	ds_write_b16 v66, v9 offset:4352
	v_mul_f32_e32 v57, v57, v79
	v_cvt_pk_bf16_f32 v57, v57, v193
	ds_write_b16 v66, v57 offset:4416
	v_mul_f32_e32 v41, v41, v79
	v_cvt_pk_bf16_f32 v41, v41, v193
	ds_write_b16 v66, v41 offset:4480
	v_mul_f32_e32 v25, v25, v79
	v_cvt_pk_bf16_f32 v25, v25, v193
	ds_write_b16 v66, v25 offset:4544
	s_waitcnt lgkmcnt(7)
	v_mul_f32_e32 v10, v10, v80
	v_cvt_pk_bf16_f32 v10, v10, v193
	ds_write_b16 v66, v10 offset:4608
	v_mul_f32_e32 v58, v58, v80
	v_cvt_pk_bf16_f32 v58, v58, v193
	ds_write_b16 v66, v58 offset:4672
	v_mul_f32_e32 v42, v42, v80
	v_cvt_pk_bf16_f32 v42, v42, v193
	ds_write_b16 v66, v42 offset:4736
	v_mul_f32_e32 v26, v26, v80
	v_cvt_pk_bf16_f32 v26, v26, v193
	ds_write_b16 v66, v26 offset:4800
	v_mul_f32_e32 v11, v11, v81
	v_cvt_pk_bf16_f32 v11, v11, v193
	ds_write_b16 v66, v11 offset:4864
	v_mul_f32_e32 v59, v59, v81
	v_cvt_pk_bf16_f32 v59, v59, v193
	ds_write_b16 v66, v59 offset:4928
	v_mul_f32_e32 v43, v43, v81
	v_cvt_pk_bf16_f32 v43, v43, v193
	ds_write_b16 v66, v43 offset:4992
	v_mul_f32_e32 v27, v27, v81
	v_cvt_pk_bf16_f32 v27, v27, v193
	ds_write_b16 v66, v27 offset:5056
	s_waitcnt lgkmcnt(7)
	v_mul_f32_e32 v12, v12, v82
	v_cvt_pk_bf16_f32 v12, v12, v193
	ds_write_b16 v66, v12 offset:6144
	v_mul_f32_e32 v60, v60, v82
	v_cvt_pk_bf16_f32 v60, v60, v193
	ds_write_b16 v66, v60 offset:6208
	v_mul_f32_e32 v44, v44, v82
	v_cvt_pk_bf16_f32 v44, v44, v193
	ds_write_b16 v66, v44 offset:6272
	v_mul_f32_e32 v28, v28, v82
	v_cvt_pk_bf16_f32 v28, v28, v193
	ds_write_b16 v66, v28 offset:6336
	v_mul_f32_e32 v13, v13, v83
	v_cvt_pk_bf16_f32 v13, v13, v193
	ds_write_b16 v66, v13 offset:6400
	v_mul_f32_e32 v61, v61, v83
	v_cvt_pk_bf16_f32 v61, v61, v193
	ds_write_b16 v66, v61 offset:6464
	v_mul_f32_e32 v45, v45, v83
	v_cvt_pk_bf16_f32 v45, v45, v193
	ds_write_b16 v66, v45 offset:6528
	v_mul_f32_e32 v29, v29, v83
	v_cvt_pk_bf16_f32 v29, v29, v193
	ds_write_b16 v66, v29 offset:6592
	s_waitcnt lgkmcnt(7)
	v_mul_f32_e32 v14, v14, v84
	v_cvt_pk_bf16_f32 v14, v14, v193
	ds_write_b16 v66, v14 offset:6656
	v_mul_f32_e32 v62, v62, v84
	v_cvt_pk_bf16_f32 v62, v62, v193
	ds_write_b16 v66, v62 offset:6720
	v_mul_f32_e32 v46, v46, v84
	v_cvt_pk_bf16_f32 v46, v46, v193
	ds_write_b16 v66, v46 offset:6784
	v_mul_f32_e32 v30, v30, v84
	v_cvt_pk_bf16_f32 v30, v30, v193
	ds_write_b16 v66, v30 offset:6848
	v_mul_f32_e32 v15, v15, v85
	v_cvt_pk_bf16_f32 v15, v15, v193
	ds_write_b16 v66, v15 offset:6912
	v_mul_f32_e32 v63, v63, v85
	v_cvt_pk_bf16_f32 v63, v63, v193
	ds_write_b16 v66, v63 offset:6976
	v_mul_f32_e32 v47, v47, v85
	v_cvt_pk_bf16_f32 v47, v47, v193
	ds_write_b16 v66, v47 offset:7040
	v_mul_f32_e32 v31, v31, v85
	v_cvt_pk_bf16_f32 v31, v31, v193
	ds_write_b16 v66, v31 offset:7104
	v_lshrrev_b32_e32 v64, 4, v177
	v_and_b32_e32 v65, 15, v177
	v_lshlrev_b32_e32 v66, 8, v178
	v_lshl_add_u32 v66, v64, 8, v66
	v_lshl_add_u32 v66, v65, 4, v66
	v_add_u32_e32 v66, 0x11000, v66
	v_add_u32_e32 v68, v178, v64
	v_mov_b32_e32 v69, 0
	v_lshlrev_b64 v[68:69], 11, v[68:69]
	v_lshl_add_u64 v[68:69], s[4:5], 0, v[68:69]
	v_lshlrev_b32_e32 v70, 4, v65
	v_mov_b32_e32 v71, 0
	v_lshl_add_u64 v[68:69], v[68:69], 0, v[70:71]
	s_waitcnt lgkmcnt(0)
	ds_read_b128 v[0:3], v66 offset:0
	ds_read_b128 v[4:7], v66 offset:1024
	ds_read_b128 v[8:11], v66 offset:2048
	ds_read_b128 v[12:15], v66 offset:3072
	ds_read_b128 v[16:19], v66 offset:4096
	ds_read_b128 v[20:23], v66 offset:5120
	ds_read_b128 v[24:27], v66 offset:6144
	ds_read_b128 v[28:31], v66 offset:7168
	s_waitcnt lgkmcnt(7)
	global_store_dwordx4 v[68:69], v[0:3], off offset:1024
	v_add_co_u32_e32 v68, vcc, 0x2000, v68
	s_nop 1
	v_addc_co_u32_e32 v69, vcc, 0, v69, vcc
	s_waitcnt lgkmcnt(6)
	global_store_dwordx4 v[68:69], v[4:7], off offset:1024
	v_add_co_u32_e32 v68, vcc, 0x2000, v68
	s_nop 1
	v_addc_co_u32_e32 v69, vcc, 0, v69, vcc
	s_waitcnt lgkmcnt(5)
	global_store_dwordx4 v[68:69], v[8:11], off offset:1024
	v_add_co_u32_e32 v68, vcc, 0x2000, v68
	s_nop 1
	v_addc_co_u32_e32 v69, vcc, 0, v69, vcc
	s_waitcnt lgkmcnt(4)
	global_store_dwordx4 v[68:69], v[12:15], off offset:1024
	v_add_co_u32_e32 v68, vcc, 0x2000, v68
	s_nop 1
	v_addc_co_u32_e32 v69, vcc, 0, v69, vcc
	s_waitcnt lgkmcnt(3)
	global_store_dwordx4 v[68:69], v[16:19], off offset:1024
	v_add_co_u32_e32 v68, vcc, 0x2000, v68
	s_nop 1
	v_addc_co_u32_e32 v69, vcc, 0, v69, vcc
	s_waitcnt lgkmcnt(2)
	global_store_dwordx4 v[68:69], v[20:23], off offset:1024
	v_add_co_u32_e32 v68, vcc, 0x2000, v68
	s_nop 1
	v_addc_co_u32_e32 v69, vcc, 0, v69, vcc
	s_waitcnt lgkmcnt(1)
	global_store_dwordx4 v[68:69], v[24:27], off offset:1024
	v_add_co_u32_e32 v68, vcc, 0x2000, v68
	s_nop 1
	v_addc_co_u32_e32 v69, vcc, 0, v69, vcc
	s_waitcnt lgkmcnt(0)
	global_store_dwordx4 v[68:69], v[28:31], off offset:1024
	s_branch .Lattn_epi_pad_end
	s_nop 0
	s_nop 0
	s_nop 0
	s_nop 0
	s_nop 0
	s_nop 0
	s_nop 0
	s_nop 0
	s_nop 0
	s_nop 0
	s_nop 0
	s_nop 0
	s_nop 0
	s_nop 0
	s_nop 0
	s_nop 0
	s_nop 0
	s_nop 0
	s_nop 0
	s_nop 0
	s_nop 0
	s_nop 0
	s_nop 0
	s_nop 0
	s_nop 0
	s_nop 0
	s_nop 0
	s_nop 0
	s_nop 0
.Lattn_epi_pad_end:
	s_mul_i32 s4, s31, s82
	s_add_i32 s14, s4, s6
	s_cmpk_lt_i32 s14, 0x480
	s_cbranch_scc0 .LBB0_358
